# baseline (speedup 1.0000x reference)
.LBB0_183:
	s_or_b64 exec, exec, s[6:7]
	s_bfe_u32 s3, s2, 0x20004
	s_and_b32 s18, s2, 15
	v_mov_b32_e32 v143, v131
	s_not_b32 s2, s2
	s_lshl_b32 s2, s2, 2
	v_ashrrev_i32_e32 v32, 6, v143
	s_lshl_b32 s6, s3, 13
	s_and_b32 s2, s2, 0x1f00
	v_lshlrev_b32_e32 v0, 5, v32
	s_or_b32 s34, s6, s2
	v_ashrrev_i32_e32 v1, 31, v0
	v_lshl_add_u64 v[132:133], s[34:35], 0, v[0:1]
	v_lshlrev_b64 v[2:3], 11, v[132:133]
	v_and_b32_e32 v148, 31, v143
	v_lshl_add_u64 v[2:3], s[12:13], 0, v[2:3]
	s_lshl_b32 s34, s18, 7
	v_bfe_u32 v146, v143, 5, 1
	v_lshl_add_u64 v[2:3], v[2:3], 0, s[34:35]
	v_lshlrev_b32_e32 v128, 11, v148
	v_lshl_add_u64 v[2:3], v[2:3], 0, v[128:129]
	v_lshlrev_b32_e32 v128, 4, v146
	v_lshl_add_u64 v[14:15], v[2:3], 0, v[128:129]
	global_load_dwordx4 v[2:5], v[14:15], off nt
	global_load_dwordx4 v[6:9], v[14:15], off offset:32 nt
	global_load_dwordx4 v[10:13], v[14:15], off offset:64 nt
	s_nop 0
	global_load_dwordx4 v[14:17], v[14:15], off offset:96 nt
	v_and_b32_e32 v1, 32, v143
	global_load_dwordx4 v[18:21], v1, s[68:69] offset:16
	global_load_dwordx4 v[22:25], v1, s[68:69]
	s_lshl_b32 s6, s3, 19
	s_add_u32 s6, s76, s6
	s_addc_u32 s7, s71, 0
	s_lshl_b32 s8, s18, 15
	s_add_u32 s38, s6, s8
	s_addc_u32 s39, s7, 0
	s_lshl_b32 s6, s2, 2
	v_and_b32_e32 v144, 63, v143
	s_mov_b64 s[8:9], 0
	s_waitcnt vmcnt(5)
	v_and_b32_e32 v27, 0xffff0000, v2
	v_lshlrev_b32_e32 v26, 16, v2
	s_waitcnt vmcnt(4)
	v_lshlrev_b32_e32 v39, 16, v8
	v_and_b32_e32 v40, 0xffff0000, v8
	v_mul_f32_e32 v8, v27, v27
	v_lshlrev_b32_e32 v28, 16, v3
	v_fmac_f32_e32 v8, v26, v26
	v_and_b32_e32 v29, 0xffff0000, v3
	v_fmac_f32_e32 v8, v28, v28
	v_lshlrev_b32_e32 v30, 16, v4
	v_fmac_f32_e32 v8, v29, v29
	v_and_b32_e32 v31, 0xffff0000, v4
	v_fmac_f32_e32 v8, v30, v30
	v_lshlrev_b32_e32 v33, 16, v5
	v_fmac_f32_e32 v8, v31, v31
	v_and_b32_e32 v34, 0xffff0000, v5
	v_fmac_f32_e32 v8, v33, v33
	v_lshlrev_b32_e32 v35, 16, v6
	v_fmac_f32_e32 v8, v34, v34
	v_and_b32_e32 v36, 0xffff0000, v6
	v_fmac_f32_e32 v8, v35, v35
	v_lshlrev_b32_e32 v37, 16, v7
	v_fmac_f32_e32 v8, v36, v36
	v_and_b32_e32 v38, 0xffff0000, v7
	v_fmac_f32_e32 v8, v37, v37
	v_fmac_f32_e32 v8, v38, v38
	v_fmac_f32_e32 v8, v39, v39
	v_lshlrev_b32_e32 v41, 16, v9
	v_fmac_f32_e32 v8, v40, v40
	v_and_b32_e32 v42, 0xffff0000, v9
	v_fmac_f32_e32 v8, v41, v41
	s_waitcnt vmcnt(3)
	v_lshlrev_b32_e32 v43, 16, v10
	v_fmac_f32_e32 v8, v42, v42
	v_and_b32_e32 v44, 0xffff0000, v10
	v_fmac_f32_e32 v8, v43, v43
	v_lshlrev_b32_e32 v45, 16, v11
	v_fmac_f32_e32 v8, v44, v44
	v_and_b32_e32 v46, 0xffff0000, v11
	v_fmac_f32_e32 v8, v45, v45
	v_lshlrev_b32_e32 v47, 16, v12
	v_fmac_f32_e32 v8, v46, v46
	v_and_b32_e32 v48, 0xffff0000, v12
	v_fmac_f32_e32 v8, v47, v47
	v_lshlrev_b32_e32 v49, 16, v13
	v_fmac_f32_e32 v8, v48, v48
	v_and_b32_e32 v50, 0xffff0000, v13
	v_fmac_f32_e32 v8, v49, v49
	s_waitcnt vmcnt(2)
	v_lshlrev_b32_e32 v51, 16, v14
	v_fmac_f32_e32 v8, v50, v50
	v_and_b32_e32 v52, 0xffff0000, v14
	v_and_b32_e32 v10, 0xffff0000, v15
	v_lshlrev_b32_e32 v11, 16, v15
	v_fmac_f32_e32 v8, v51, v51
	v_mul_f32_e64 v2, v10, v10
	v_mul_f32_e64 v3, v11, v11
	v_fmac_f32_e32 v8, v52, v52
	v_and_b32_e32 v12, 0xffff0000, v16
	v_lshlrev_b32_e32 v13, 16, v16
	v_add_f32_e32 v3, v3, v8
	v_mul_f32_e64 v4, v12, v12
	v_mul_f32_e64 v5, v13, v13
	v_add_f32_e32 v2, v2, v3
	v_and_b32_e32 v14, 0xffff0000, v17
	v_lshlrev_b32_e32 v15, 16, v17
	v_add_f32_e32 v2, v5, v2
	v_mul_f32_e64 v6, v14, v14
	v_mul_f32_e64 v7, v15, v15
	v_add_f32_e32 v2, v4, v2
	v_add_f32_e32 v2, v7, v2
	v_add_f32_e32 v2, v6, v2
	v_mov_b32_e32 v3, v2
	s_nop 1
	v_permlane32_swap_b32_e32 v2, v3
	v_add_f32_e32 v2, v2, v3
	v_fmamk_f32 v2, v2, 0x3c800000, v130
	v_mul_f32_e32 v3, 0x4b800000, v2
	v_cmp_gt_f32_e32 vcc, s89, v2
	s_nop 1
	v_cndmask_b32_e32 v2, v2, v3, vcc
	v_rsq_f32_e32 v2, v2
	s_nop 0
	v_mul_f32_e32 v3, 0x45800000, v2
	v_cndmask_b32_e32 v16, v2, v3, vcc
	v_mul_f32_e32 v2, v16, v26
	v_mul_f32_e32 v3, v16, v27
	v_mul_f32_e32 v4, v16, v28
	v_mul_f32_e32 v5, v16, v29
	v_mul_f32_e32 v6, v16, v30
	v_mul_f32_e32 v7, v16, v31
	v_mul_f32_e32 v8, v16, v33
	v_mul_f32_e32 v9, v16, v34
	s_waitcnt vmcnt(0)
	v_mul_f32_e32 v2, v22, v2
	v_mul_f32_e32 v3, v23, v3
	v_mul_f32_e32 v4, v24, v4
	v_mul_f32_e32 v5, v25, v5
	v_mul_f32_e32 v6, v18, v6
	v_mul_f32_e32 v7, v19, v7
	v_mul_f32_e32 v8, v20, v8
	v_mul_f32_e32 v9, v21, v9
	v_cvt_pk_bf16_f32 v96, v2, v3
	v_cvt_pk_bf16_f32 v97, v4, v5
	v_cvt_pk_bf16_f32 v98, v6, v7
	v_cvt_pk_bf16_f32 v99, v8, v9
	global_load_dwordx4 v[2:5], v1, s[68:69] offset:64
	global_load_dwordx4 v[6:9], v1, s[68:69] offset:80
	v_mul_f32_e32 v17, v16, v35
	v_mul_f32_e32 v18, v16, v36
	v_mul_f32_e32 v19, v16, v37
	v_mul_f32_e32 v20, v16, v38
	v_mul_f32_e32 v21, v16, v39
	v_mul_f32_e32 v22, v16, v40
	v_mul_f32_e32 v23, v16, v41
	v_mul_f32_e32 v24, v16, v42
	v_mul_f32_e32 v11, v16, v11
	v_mul_f32_e32 v10, v16, v10
	v_mul_f32_e32 v13, v16, v13
	v_mul_f32_e32 v12, v16, v12
	v_mul_f32_e32 v15, v16, v15
	v_mul_f32_e32 v14, v16, v14
	s_waitcnt vmcnt(1)
	v_mul_f32_e32 v2, v2, v17
	v_mul_f32_e32 v3, v3, v18
	v_mul_f32_e32 v4, v4, v19
	v_mul_f32_e32 v5, v5, v20
	s_waitcnt vmcnt(0)
	v_mul_f32_e32 v6, v6, v21
	v_mul_f32_e32 v7, v7, v22
	v_mul_f32_e32 v8, v8, v23
	v_mul_f32_e32 v9, v9, v24
	v_cvt_pk_bf16_f32 v100, v2, v3
	v_cvt_pk_bf16_f32 v101, v4, v5
	v_cvt_pk_bf16_f32 v102, v6, v7
	v_cvt_pk_bf16_f32 v103, v8, v9
	global_load_dwordx4 v[2:5], v1, s[68:69] offset:128
	global_load_dwordx4 v[6:9], v1, s[68:69] offset:144
	v_mul_f32_e32 v17, v16, v43
	v_mul_f32_e32 v18, v16, v44
	v_mul_f32_e32 v19, v16, v45
	v_mul_f32_e32 v20, v16, v46
	v_mul_f32_e32 v21, v16, v47
	v_mul_f32_e32 v22, v16, v48
	v_mul_f32_e32 v23, v16, v49
	v_mul_f32_e32 v24, v16, v50
	s_waitcnt vmcnt(1)
	v_mul_f32_e32 v2, v17, v2
	v_mul_f32_e32 v3, v18, v3
	v_mul_f32_e32 v4, v19, v4
	v_mul_f32_e32 v5, v20, v5
	s_waitcnt vmcnt(0)
	v_mul_f32_e32 v6, v21, v6
	v_mul_f32_e32 v7, v22, v7
	v_mul_f32_e32 v8, v23, v8
	v_mul_f32_e32 v9, v24, v9
	v_cvt_pk_bf16_f32 v104, v2, v3
	v_cvt_pk_bf16_f32 v105, v4, v5
	v_cvt_pk_bf16_f32 v106, v6, v7
	v_cvt_pk_bf16_f32 v107, v8, v9
	global_load_dwordx4 v[2:5], v1, s[68:69] offset:192
	global_load_dwordx4 v[6:9], v1, s[68:69] offset:208
	v_mov_b32_e32 v1, s6
	v_mul_f32_e32 v17, v16, v51
	v_mul_f32_e32 v18, v16, v52
	s_add_i32 s6, s2, 0x100
	s_lshr_b32 s77, s6, 6
	v_cmp_gt_u32_e32 vcc, s77, v144
	s_mov_b64 s[6:7], 0
	s_waitcnt vmcnt(1)
	v_mul_f32_e32 v2, v17, v2
	v_mul_f32_e32 v3, v18, v3
	v_mul_f32_e32 v4, v11, v4
	v_mul_f32_e32 v5, v10, v5
	s_waitcnt vmcnt(0)
	v_mul_f32_e32 v6, v13, v6
	v_mul_f32_e32 v7, v12, v7
	v_mul_f32_e32 v8, v15, v8
	v_mul_f32_e32 v9, v14, v9
	v_cvt_pk_bf16_f32 v108, v2, v3
	v_cvt_pk_bf16_f32 v109, v4, v5
	v_cvt_pk_bf16_f32 v110, v6, v7
	v_cvt_pk_bf16_f32 v111, v8, v9
	global_load_dword v1, v1, s[38:39]
	s_and_saveexec_b64 s[10:11], vcc
	s_cbranch_execz .LBB0_185
	v_lshlrev_b32_e32 v2, 8, v144
	global_load_dword v2, v2, s[38:39] offset:252
	s_waitcnt vmcnt(0)
	v_sub_f32_e32 v2, v2, v1
	v_mul_f32_e32 v2, 0x3e000000, v2
	v_cmp_lt_f32_e64 s[8:9], v2, -v142
	s_and_b64 s[8:9], s[8:9], exec

.LBB0_193:
	s_nop 7
	v_max_f32_e32 v34, v17, v17
	v_max_f32_e32 v35, v16, v16
	v_max_f32_e32 v34, v35, v34
	v_max3_f32 v34, v34, v18, v19
	v_max3_f32 v34, v34, v20, v21
	v_max3_f32 v34, v34, v22, v23
	v_max3_f32 v34, v34, v24, v25
	v_max3_f32 v34, v34, v26, v27
	v_max3_f32 v34, v34, v28, v29
	v_max3_f32 v34, v34, v30, v31
	v_max3_f32 v34, v34, v0, v1
	v_max3_f32 v34, v34, v2, v3
	v_max3_f32 v34, v34, v4, v5
	v_max3_f32 v34, v34, v6, v7
	v_max3_f32 v34, v34, v8, v9
	v_max3_f32 v34, v34, v10, v11
	v_max3_f32 v34, v34, v12, v13
	v_max3_f32 v34, v34, v14, v15
	v_mov_b32_e32 v35, v34
	s_nop 1
	v_permlane32_swap_b32_e32 v34, v35
	v_max_f32_e32 v35, v35, v35
	v_max_f32_e32 v34, v34, v34
	v_max_f32_e32 v34, v34, v35
	v_add_f32_e32 v35, 0x7149f2ca, v34
	v_mul_f32_e32 v35, 0x3e000000, v35
	s_mov_b32 s8, 0x41800000
	v_cmp_ge_f32_e32 vcc, s8, v35
	s_cmp_eq_u64 vcc, exec
	s_cselect_b64 vcc, -1, 0
	v_cmp_lt_i32_e64 s[8:9], 3, v32
	s_and_saveexec_b64 s[10:11], s[8:9]
	s_setprio 1
	s_or_b64 exec, exec, s[10:11]
	v_max_f32_e32 v34, 0xf149f2ca, v34
	v_mov_b32_e32 v32, 0xf149f2ca
	v_cndmask_b32_e32 v163, v34, v32, vcc
	v_mul_f32_e32 v32, 0xbe38aa3b, v163
	v_fmamk_f32 v16, v16, 0x3e38aa3b, v32
	v_exp_f32_e32 v188, v16
	v_sub_f32_e32 v16, 0xf149f2ca, v34
	v_mul_f32_e32 v16, 0x3e38aa3b, v16
	v_fmamk_f32 v17, v17, 0x3e38aa3b, v32
	v_fmamk_f32 v18, v18, 0x3e38aa3b, v32
	v_fmamk_f32 v19, v19, 0x3e38aa3b, v32
	v_fmamk_f32 v20, v20, 0x3e38aa3b, v32
	v_fmamk_f32 v21, v21, 0x3e38aa3b, v32
	v_fmamk_f32 v22, v22, 0x3e38aa3b, v32
	v_fmamk_f32 v23, v23, 0x3e38aa3b, v32
	v_fmamk_f32 v24, v24, 0x3e38aa3b, v32
	v_fmamk_f32 v25, v25, 0x3e38aa3b, v32
	v_fmamk_f32 v26, v26, 0x3e38aa3b, v32
	v_fmamk_f32 v27, v27, 0x3e38aa3b, v32
	v_fmamk_f32 v28, v28, 0x3e38aa3b, v32
	v_fmamk_f32 v29, v29, 0x3e38aa3b, v32
	v_fmamk_f32 v30, v30, 0x3e38aa3b, v32
	v_fmamk_f32 v31, v31, 0x3e38aa3b, v32
	v_exp_f32_e32 v16, v16
	v_exp_f32_e32 v190, v17
	v_exp_f32_e32 v186, v18
	v_exp_f32_e32 v189, v19
	v_exp_f32_e32 v184, v20
	v_exp_f32_e32 v187, v21
	v_exp_f32_e32 v183, v22
	v_exp_f32_e32 v185, v23
	v_exp_f32_e32 v171, v24
	v_exp_f32_e32 v180, v25
	v_exp_f32_e32 v170, v26
	v_exp_f32_e32 v172, v27
	v_exp_f32_e32 v169, v28
	v_exp_f32_e32 v182, v29
	v_exp_f32_e32 v173, v30
	v_exp_f32_e32 v181, v31
	v_fma_f32 v138, v2, s82, v32
	v_fma_f32 v139, v3, s82, v32
	v_fma_f32 v140, v0, s82, v32
	v_fma_f32 v141, v1, s82, v32
	v_and_b32_e32 v0, 0x3fffffc0, v143
	v_lshlrev_b32_e32 v2, 6, v143
	v_lshlrev_b32_e32 v0, 2, v0
	v_and_b32_e32 v1, 0x78, v33
	v_and_b32_e32 v2, 0x400, v2
	v_lshlrev_b32_e32 v3, 8, v146
	s_add_i32 s8, s3, 2
	v_cndmask_b32_e64 v149, v16, 1.0, vcc
	v_fma_f32 v86, v14, s82, v32
	v_fma_f32 v87, v15, s82, v32
	v_fma_f32 v88, v12, s82, v32
	v_fma_f32 v89, v13, s82, v32
	v_fma_f32 v90, v10, s82, v32
	v_fma_f32 v91, v11, s82, v32
	v_fma_f32 v94, v8, s82, v32
	v_fma_f32 v95, v9, s82, v32
	v_fma_f32 v134, v6, s82, v32
	v_fma_f32 v135, v7, s82, v32
	v_fma_f32 v136, v4, s82, v32
	v_fma_f32 v137, v5, s82, v32
	v_or3_b32 v151, v1, v2, v3
	s_cmp_ge_i32 s8, s77
	v_cmp_gt_u32_e64 s[8:9], 32, v144
	v_lshl_add_u32 v147, v148, 2, v0
	v_lshl_add_u32 v145, v157, 2, v0
	s_cbranch_scc1 .LBB0_221
	v_mov_b32_e32 v150, 0
	s_mov_b64 s[92:93], s[14:15]
	s_mov_b64 s[14:15], s[12:13]
	s_mov_b32 s12, s71
	s_mov_b32 s71, s46
	s_mov_b32 s70, s37
	s_mov_b32 s10, 2
	v_subrev_u32_e32 v128, s2, v157
	s_mov_b32 s2, 0
	s_sub_i32 s18, 0, s77
	s_add_i32 s19, s3, 3
	s_mov_b32 s86, 1
	v_mov_b32_e32 v166, v144
	v_mov_b32_e32 v16, 0
	v_mov_b32_e32 v17, v150
	v_mov_b32_e32 v18, v150
	v_mov_b32_e32 v19, v150
	v_mov_b32_e32 v20, v150
	v_mov_b32_e32 v21, v150
	v_mov_b32_e32 v22, v150
	v_mov_b32_e32 v23, v150
	v_mov_b32_e32 v24, v150
	v_mov_b32_e32 v25, v150
	v_mov_b32_e32 v26, v150
	v_mov_b32_e32 v27, v150
	v_mov_b32_e32 v28, v150
	v_mov_b32_e32 v29, v150
	v_mov_b32_e32 v30, v150
	v_mov_b32_e32 v31, v150
	v_mov_b32_e32 v0, 0
	v_mov_b32_e32 v1, v150
	v_mov_b32_e32 v2, v150
	v_mov_b32_e32 v3, v150
	v_mov_b32_e32 v4, v150
	v_mov_b32_e32 v5, v150
	v_mov_b32_e32 v6, v150
	v_mov_b32_e32 v7, v150
	v_mov_b32_e32 v8, v150
	v_mov_b32_e32 v9, v150
	v_mov_b32_e32 v10, v150
	v_mov_b32_e32 v11, v150
	v_mov_b32_e32 v12, v150
	v_mov_b32_e32 v13, v150
	v_mov_b32_e32 v14, v150
	v_mov_b32_e32 v15, v150

.LBB0_203:
	s_or_b64 exec, exec, s[36:37]
	v_max_f32_e32 v64, v64, v64
	v_max_f32_e32 v65, v163, v163
	v_max_f32_e32 v136, v65, v64
	v_sub_f32_e32 v64, v163, v136
	v_mul_f32_e32 v64, 0x3e38aa3b, v64
	v_exp_f32_e32 v64, v64
	s_cmp_eq_u64 vcc, s[10:11]
	s_cselect_b64 s[10:11], -1, 0
	v_cndmask_b32_e64 v191, v64, 1.0, s[10:11]
	v_cmp_gt_f32_e32 vcc, 1.0, v191
	s_cbranch_vccz .LBB0_207
	s_and_saveexec_b64 s[36:37], s[8:9]
	ds_write_b32 v147, v191 offset:49280
	s_or_b64 exec, exec, s[36:37]
	s_waitcnt lgkmcnt(0)
	ds_read_b128 v[64:67], v145 offset:49376
	ds_read_b128 v[68:71], v145 offset:49344
	ds_read_b128 v[72:75], v145 offset:49312
	ds_read_b128 v[76:79], v145 offset:49280
	s_waitcnt lgkmcnt(3)
	v_mul_f32_e64 v30, v30, v66
	v_mul_f32_e64 v31, v31, v67
	s_waitcnt lgkmcnt(2)
	v_mul_f32_e64 v26, v26, v70
	v_mul_f32_e64 v27, v27, v71
	s_waitcnt lgkmcnt(1)
	v_mul_f32_e64 v22, v22, v74
	v_mul_f32_e64 v23, v23, v75
	s_waitcnt lgkmcnt(0)
	v_mul_f32_e64 v18, v18, v78
	v_mul_f32_e64 v19, v19, v79
	v_mul_f32_e64 v28, v28, v64
	v_mul_f32_e64 v29, v29, v65
	v_mul_f32_e64 v24, v24, v68
	v_mul_f32_e64 v25, v25, v69
	v_mul_f32_e64 v20, v20, v72
	v_mul_f32_e64 v21, v21, v73
	v_mul_f32_e64 v16, v16, v76
	v_mul_f32_e64 v17, v17, v77
	v_mul_f32_e64 v14, v14, v66
	v_mul_f32_e64 v15, v15, v67
	v_mul_f32_e64 v10, v10, v70
	v_mul_f32_e64 v11, v11, v71
	v_mul_f32_e64 v6, v6, v74
	v_mul_f32_e64 v7, v7, v75
	v_mul_f32_e64 v2, v2, v78
	v_mul_f32_e64 v3, v3, v79
	v_mul_f32_e64 v12, v12, v64
	v_mul_f32_e64 v13, v13, v65
	v_mul_f32_e64 v8, v8, v68
	v_mul_f32_e64 v9, v9, v69
	v_mul_f32_e64 v4, v4, v72
	v_mul_f32_e64 v5, v5, v73
	v_mul_f32_e64 v0, v0, v76
	v_mul_f32_e64 v1, v1, v77

.LBB0_215:
	v_max_f32_e32 v33, v136, v136
	v_max_f32_e32 v32, v33, v32
	v_sub_f32_e32 v33, v136, v32
	v_mul_f32_e32 v33, 0x3e38aa3b, v33
	v_exp_f32_e32 v33, v33
	s_nop 0
	v_cndmask_b32_e64 v33, v33, 1.0, s[10:11]
	v_cmp_gt_f32_e32 vcc, 1.0, v33
	s_cbranch_vccz .LBB0_219
	s_and_saveexec_b64 s[22:23], s[8:9]
	ds_write_b32 v147, v33 offset:49280
	s_or_b64 exec, exec, s[22:23]
	s_waitcnt lgkmcnt(0)
	ds_read_b128 v[34:37], v145 offset:49376
	ds_read_b128 v[38:41], v145 offset:49344
	ds_read_b128 v[42:45], v145 offset:49312
	ds_read_b128 v[50:53], v145 offset:49280
	s_waitcnt lgkmcnt(3)
	v_mul_f32_e64 v30, v30, v36
	v_mul_f32_e64 v31, v31, v37
	s_waitcnt lgkmcnt(2)
	v_mul_f32_e64 v26, v26, v40
	v_mul_f32_e64 v27, v27, v41
	s_waitcnt lgkmcnt(1)
	v_mul_f32_e64 v22, v22, v44
	v_mul_f32_e64 v23, v23, v45
	s_waitcnt lgkmcnt(0)
	v_mul_f32_e64 v18, v18, v52
	v_mul_f32_e64 v19, v19, v53
	v_mul_f32_e64 v28, v28, v34
	v_mul_f32_e64 v29, v29, v35
	v_mul_f32_e64 v24, v24, v38
	v_mul_f32_e64 v25, v25, v39
	v_mul_f32_e64 v20, v20, v42
	v_mul_f32_e64 v21, v21, v43
	v_mul_f32_e64 v16, v16, v50
	v_mul_f32_e64 v17, v17, v51
	v_mul_f32_e64 v14, v14, v36
	v_mul_f32_e64 v15, v15, v37
	v_mul_f32_e64 v10, v10, v40
	v_mul_f32_e64 v11, v11, v41
	v_mul_f32_e64 v6, v6, v44
	v_mul_f32_e64 v7, v7, v45
	v_mul_f32_e64 v2, v2, v52
	v_mul_f32_e64 v3, v3, v53
	v_mul_f32_e64 v12, v12, v34
	v_mul_f32_e64 v13, v13, v35
	v_mul_f32_e64 v8, v8, v38
	v_mul_f32_e64 v9, v9, v39
	v_mul_f32_e64 v4, v4, v42
	v_mul_f32_e64 v5, v5, v43
	v_mul_f32_e64 v0, v0, v50
	v_mul_f32_e64 v1, v1, v51
.LBB0_219:
	v_cndmask_b32_e64 v163, v32, v136, s[10:11]
	v_mul_f32_e32 v32, 0xbe38aa3b, v163
	v_fmamk_f32 v34, v80, 0x3e38aa3b, v32
	v_fmamk_f32 v35, v81, 0x3e38aa3b, v32
	v_fmamk_f32 v36, v82, 0x3e38aa3b, v32
	v_fmamk_f32 v37, v83, 0x3e38aa3b, v32
	v_fmamk_f32 v38, v84, 0x3e38aa3b, v32
	v_fmamk_f32 v39, v85, 0x3e38aa3b, v32
	v_fmamk_f32 v40, v86, 0x3e38aa3b, v32
	v_fmamk_f32 v41, v87, 0x3e38aa3b, v32
	v_fmamk_f32 v42, v88, 0x3e38aa3b, v32
	v_fmamk_f32 v43, v89, 0x3e38aa3b, v32
	v_fmamk_f32 v44, v90, 0x3e38aa3b, v32
	v_fmamk_f32 v45, v91, 0x3e38aa3b, v32
	v_fmamk_f32 v46, v92, 0x3e38aa3b, v32
	v_fmamk_f32 v47, v93, 0x3e38aa3b, v32
	v_fmamk_f32 v50, v94, 0x3e38aa3b, v32
	v_fmamk_f32 v51, v95, 0x3e38aa3b, v32
	v_exp_f32_e32 v188, v34
	v_exp_f32_e32 v190, v35
	v_exp_f32_e32 v186, v36
	v_exp_f32_e32 v189, v37
	v_exp_f32_e32 v184, v38
	v_exp_f32_e32 v187, v39
	v_exp_f32_e32 v183, v40
	v_exp_f32_e32 v185, v41
	v_exp_f32_e32 v171, v42
	v_exp_f32_e32 v180, v43
	v_exp_f32_e32 v170, v44
	v_exp_f32_e32 v172, v45
	v_exp_f32_e32 v169, v46
	v_exp_f32_e32 v182, v47
	v_exp_f32_e32 v173, v50
	v_exp_f32_e32 v181, v51
	v_fma_f32 v86, v78, s82, v32
	v_fma_f32 v87, v79, s82, v32
	v_fma_f32 v88, v76, s82, v32
	v_fma_f32 v89, v77, s82, v32
	v_fma_f32 v90, v74, s82, v32
	v_fma_f32 v91, v75, s82, v32
	v_fma_f32 v94, v72, s82, v32
	v_fma_f32 v95, v73, s82, v32
	v_fma_f32 v134, v70, s82, v32
	v_fma_f32 v135, v71, s82, v32
	v_fma_f32 v136, v68, s82, v32
	v_fma_f32 v137, v69, s82, v32
	v_fma_f32 v138, v66, s82, v32
	v_fma_f32 v139, v67, s82, v32
	v_fma_f32 v140, v64, s82, v32
	v_fma_f32 v141, v65, s82, v32
	v_add_f32_e32 v32, v167, v168
	v_fmac_f32_e32 v32, v149, v150
	v_add_f32_e32 v150, v48, v49
	s_add_i32 s19, s19, 2
	v_fmac_f32_e32 v150, v32, v191
	v_add_u32_e32 v128, 0x80, v128
	v_add_u32_e32 v166, 0x80, v166
	s_cmp_ge_i32 s36, s77
	v_add_u32_e32 v158, 0x80, v158
	s_waitcnt lgkmcnt(0)
	s_barrier
	s_cbranch_scc1 .LBB0_222
	s_mov_b32 s10, s86
	s_mov_b32 s86, s2
	s_mov_b32 s2, s79
	v_mov_b32_e32 v149, v33
	s_branch .LBB0_197

.LBB0_224:
	v_readlane_b32 s86, v255, 11
	v_readlane_b32 s87, v255, 12
	s_movk_i32 s34, 0x2000
	v_cmp_gt_f32_e32 vcc, 1.0, v63
	s_cbranch_vccz .LBB0_228
	v_cmp_gt_u32_e32 vcc, 32, v144
	s_and_saveexec_b64 s[6:7], vcc
	ds_write_b32 v147, v63 offset:49280
	s_or_b64 exec, exec, s[6:7]
	s_waitcnt lgkmcnt(0)
	ds_read_b128 v[86:89], v145 offset:49376
	ds_read_b128 v[100:103], v145 offset:49344
	ds_read_b128 v[104:107], v145 offset:49312
	ds_read_b128 v[108:111], v145 offset:49280
	s_waitcnt lgkmcnt(3)
	v_mul_f32_e64 v30, v30, v88
	v_mul_f32_e64 v31, v31, v89
	s_waitcnt lgkmcnt(2)
	v_mul_f32_e64 v26, v26, v102
	v_mul_f32_e64 v27, v27, v103
	s_waitcnt lgkmcnt(1)
	v_mul_f32_e64 v22, v22, v106
	v_mul_f32_e64 v23, v23, v107
	s_waitcnt lgkmcnt(0)
	v_mul_f32_e64 v18, v18, v110
	v_mul_f32_e64 v19, v19, v111
	v_mul_f32_e64 v28, v28, v86
	v_mul_f32_e64 v29, v29, v87
	v_mul_f32_e64 v24, v24, v100
	v_mul_f32_e64 v25, v25, v101
	v_mul_f32_e64 v20, v20, v104
	v_mul_f32_e64 v21, v21, v105
	v_mul_f32_e64 v16, v16, v108
	v_mul_f32_e64 v17, v17, v109
	v_mul_f32_e64 v14, v14, v88
	v_mul_f32_e64 v15, v15, v89
	v_mul_f32_e64 v10, v10, v102
	v_mul_f32_e64 v11, v11, v103
	v_mul_f32_e64 v6, v6, v106
	v_mul_f32_e64 v7, v7, v107
	v_mul_f32_e64 v2, v2, v110
	v_mul_f32_e64 v3, v3, v111
	v_mul_f32_e64 v12, v12, v86
	v_mul_f32_e64 v13, v13, v87
	v_mul_f32_e64 v8, v8, v100
	v_mul_f32_e64 v9, v9, v101
	v_mul_f32_e64 v4, v4, v104
	v_mul_f32_e64 v5, v5, v105
	v_mul_f32_e64 v0, v0, v108
	v_mul_f32_e64 v1, v1, v109
